# v16 with the attention static priority raise on waves 0-3 instead of 4-7
# speedup vs baseline: 1.0027x; 1.0027x over previous
; #define SBAR() __builtin_amdgcn_sched_barrier(0)
; #define VMW() asm volatile("s_waitcnt vmcnt(0)" ::: "memory")
; #define SWRITE_H(bf) do { SWRITE_HV(bf); SWRITE_HK(bf); } while (0)
; #define MASKT(P0_, P1_, t) do { const int kb_ = KBASE(t); if (kb_ + KVBLK - 1 > qlo) mask_tile(P0_, P1_, qm - kb_); } while (0)
; __device__ __forceinline__ void partialSM(f32x16& p0, f32x16& p1, float& m_reg, float& mn, float& alpha) {
;     float pmax = p0[0];
; #pragma unroll
;     for (int r = 1; r < 16; ++r) pmax = fmaxf(pmax, p0[r]);
; #pragma unroll
;     for (int r = 0; r < 16; ++r) pmax = fmaxf(pmax, p1[r]);
;     { auto rr = __builtin_amdgcn_permlane32_swap(__float_as_uint(pmax), __float_as_uint(pmax), false, false);
;       pmax = fmaxf(__uint_as_float(rr[0]), __uint_as_float(rr[1])); }
;     constexpr float C2 = 1.4426950408889634f * SCALE;
;     if (__builtin_expect(__all((pmax - m_reg) * SCALE <= THR), 1)) { mn = m_reg; alpha = 1.f; }
;     else { mn = fmaxf(m_reg, pmax); alpha = __builtin_amdgcn_exp2f((m_reg - mn) * C2); m_reg = mn; }
;     const float mnL = -mn * C2;
; #pragma unroll
;     for (int r = 0; r < 16; ++r) p0[r] = fmaf(p0[r], C2, mnL);
; #pragma unroll
;     for (int r = 0; r < 16; ++r) p1[r] = fmaf(p1[r], C2, mnL);
; #pragma unroll
;     for (int r = 0; r < 16; ++r) p0[r] = __builtin_amdgcn_exp2f(p0[r]);
; }
; __device__ __forceinline__ void attn_block(const BlockRef& cur, const BlockRef& nxt, char* lds, Seam& S) {
;     ...
;     SBAR(); qkt<0>(pA0, pA1, K_lds, r32, hi, S.qr, qx);
;     MASKT(pA0, pA1, 0); partialSM(pA0, pA1, m_reg, mnA, alA);
;     if (NT > 1) { VMW(); SWRITE_H(1); }
;     __syncthreads();
.LBB0_969:
	v_max_f32_e32 v33, 0xf149f2ca, v32
	v_cndmask_b32_e64 v148, v33, v199, s[0:1]
	v_mul_f32_e32 v32, 0xbdd53b94, v148
	v_fmamk_f32 v16, v16, 0x3dd53b94, v32
	v_exp_f32_e32 v159, v16
	v_sub_f32_e32 v16, 0xf149f2ca, v33
	v_mul_f32_e32 v16, 0x3dd53b94, v16
	v_exp_f32_e32 v16, v16
	v_fmamk_f32 v17, v17, 0x3dd53b94, v32
	v_fmamk_f32 v18, v18, 0x3dd53b94, v32
	v_fmamk_f32 v19, v19, 0x3dd53b94, v32
	v_fmamk_f32 v20, v20, 0x3dd53b94, v32
	v_fmamk_f32 v21, v21, 0x3dd53b94, v32
	v_fmamk_f32 v22, v22, 0x3dd53b94, v32
	v_fmamk_f32 v23, v23, 0x3dd53b94, v32
	v_fmamk_f32 v24, v24, 0x3dd53b94, v32
	v_fmamk_f32 v25, v25, 0x3dd53b94, v32
	v_fmamk_f32 v26, v26, 0x3dd53b94, v32
	v_fmamk_f32 v27, v27, 0x3dd53b94, v32
	v_fmamk_f32 v28, v28, 0x3dd53b94, v32
	v_fmamk_f32 v29, v29, 0x3dd53b94, v32
	v_fmamk_f32 v30, v30, 0x3dd53b94, v32
	v_fmamk_f32 v31, v31, 0x3dd53b94, v32
	v_cndmask_b32_e64 v209, v16, 1.0, s[0:1]
	s_and_b32 s0, s94, 0x3fffffc0
	v_exp_f32_e32 v161, v17
	v_exp_f32_e32 v157, v18
	v_exp_f32_e32 v160, v19
	v_exp_f32_e32 v156, v20
	v_exp_f32_e32 v158, v21
	v_exp_f32_e32 v154, v22
	v_exp_f32_e32 v155, v23
	v_exp_f32_e32 v150, v24
	v_exp_f32_e32 v153, v25
	s_waitcnt vmcnt(4)
	v_exp_f32_e32 v146, v26
	v_exp_f32_e32 v151, v27
	v_exp_f32_e32 v144, v28
	v_exp_f32_e32 v152, v29
	v_exp_f32_e32 v145, v30
	v_exp_f32_e32 v147, v31
	s_lshl_b32 s0, s0, 2
	s_add_i32 s0, s0, 0
	s_add_i32 s1, s68, 0x100
	s_add_i32 s0, s0, 0x14000
	s_waitcnt vmcnt(2)
	v_pk_fma_f32 v[128:129], v[14:15], s[90:91], v[32:33] op_sel_hi:[1,0,0]
	v_pk_fma_f32 v[130:131], v[12:13], s[90:91], v[32:33] op_sel_hi:[1,0,0]
	v_pk_fma_f32 v[132:133], v[10:11], s[90:91], v[32:33] op_sel_hi:[1,0,0]
	v_pk_fma_f32 v[134:135], v[8:9], s[90:91], v[32:33] op_sel_hi:[1,0,0]
	s_waitcnt vmcnt(1)
	v_pk_fma_f32 v[136:137], v[6:7], s[90:91], v[32:33] op_sel_hi:[1,0,0]
	v_pk_fma_f32 v[138:139], v[4:5], s[90:91], v[32:33] op_sel_hi:[1,0,0]
	s_waitcnt vmcnt(0)
	v_pk_fma_f32 v[140:141], v[2:3], s[90:91], v[32:33] op_sel_hi:[1,0,0]
	v_pk_fma_f32 v[142:143], v[0:1], s[90:91], v[32:33] op_sel_hi:[1,0,0]
	v_mov_b32_e32 v15, 0
	s_cmpk_lt_i32 s68, 0xffc0
	v_lshl_add_u32 v201, v167, 2, s0
	v_lshl_add_u32 v175, v183, 2, s0
	s_waitcnt lgkmcnt(0)
	s_barrier
	s_cbranch_scc1 .LBB0_989
	v_readfirstlane_b32 s8, v168
	s_nop 3
	s_cmp_lt_u32 s8, 0x100
	s_cbranch_scc0 .Lattn_prio_done
	s_setprio 1
